# next phase's code prefetched into the XCC's L2 by the barrier leader during each seam wait (data-side touches of the instruction bytes)
# speedup vs baseline: 1.0050x; 1.0050x over previous
.Lxb0_top:
	s_waitcnt vmcnt(0) lgkmcnt(0)
	v_mov_b32_e32 v1, 1
	s_getreg_b32 s10, hwreg(HW_REG_XCC_ID, 0, 4)
	s_and_b32 s10, s10, 15
	v_mov_b32_e32 v0, 0x400
	s_mov_b32 s11, 0

.Lxb0_wait:
	s_getpc_b64 s[10:11]
.Lxb0_ic:
	s_add_u32 s10, s10, .Lxb0_done-.Lxb0_ic
	s_addc_u32 s11, s11, 0
	s_mov_b32 s12, .Lxb1_top-.Lxb0_done
	s_add_u32 s12, s12, 4095
	s_lshr_b32 s12, s12, 12
	s_mov_b64 exec, -1
	v_mbcnt_lo_u32_b32 v8, -1, 0
	v_mbcnt_hi_u32_b32 v8, -1, v8
	v_lshlrev_b32_e32 v8, 6, v8
.Lxb0_icl:
	global_load_dword v9, v8, s[10:11]
	s_add_u32 s10, s10, 0x1000
	s_addc_u32 s11, s11, 0
	s_sub_u32 s12, s12, 1
	s_cmp_lg_u32 s12, 0
	s_cbranch_scc1 .Lxb0_icl
	s_mov_b64 exec, 1
	s_mov_b32 s11, 0

.Lxb1_top:
	s_waitcnt vmcnt(0) lgkmcnt(0)
	v_mov_b32_e32 v1, 1
	v_readlane_b32 s11, v244, 43
	s_cmp_eq_u32 s11, 1
	s_cbranch_scc0 .Lxb1_glob
	s_and_b32 s12, s2, 7
	s_lshl_b32 s10, s12, 8
	s_add_i32 s10, s10, 0x6000
	v_mov_b32_e32 v6, s10
	global_atomic_add v6, v1, s[92:93]
	buffer_inv sc1
	v_readlane_b32 s11, v244, 41
	s_sub_i32 s11, s11, s12
	s_add_i32 s11, s11, 7
	s_lshr_b32 s11, s11, 3
	s_mul_i32 s6, s11, 1
	s_branch .Lxb1_wait

.Lxb2_top:
	s_waitcnt vmcnt(0) lgkmcnt(0)
	v_mov_b32_e32 v1, 1
	v_readlane_b32 s11, v244, 43
	s_cmp_eq_u32 s11, 1
	s_cbranch_scc0 .Lxb2_glob
	s_and_b32 s12, s2, 7
	s_lshl_b32 s10, s12, 8
	s_add_i32 s10, s10, 0x6000
	v_mov_b32_e32 v6, s10
	global_atomic_add v6, v1, s[92:93]
	buffer_inv sc1
	v_readlane_b32 s11, v244, 41
	s_sub_i32 s11, s11, s12
	s_add_i32 s11, s11, 7
	s_lshr_b32 s11, s11, 3
	s_mul_i32 s6, s11, 2
	s_branch .Lxb2_wait

.Lxb3_top:
	s_waitcnt vmcnt(0) lgkmcnt(0)
	v_mov_b32_e32 v1, 1
	v_readlane_b32 s11, v244, 43
	s_cmp_eq_u32 s11, 1
	s_cbranch_scc0 .Lxb3_glob
	s_and_b32 s12, s2, 7
	s_lshl_b32 s10, s12, 8
	s_add_i32 s10, s10, 0x6000
	v_mov_b32_e32 v6, s10
	global_atomic_add v6, v1, s[92:93]
	buffer_inv sc1
	v_readlane_b32 s11, v244, 41
	s_sub_i32 s11, s11, s12
	s_add_i32 s11, s11, 7
	s_lshr_b32 s11, s11, 3
	s_mul_i32 s6, s11, 3
	s_branch .Lxb3_wait

.Lxb4_top:
	s_waitcnt vmcnt(0) lgkmcnt(0)
	v_mov_b32_e32 v1, 1
	v_readlane_b32 s11, v244, 43
	s_cmp_eq_u32 s11, 1
	s_cbranch_scc0 .Lxb4_glob
	s_and_b32 s12, s2, 7
	s_lshl_b32 s10, s12, 8
	s_add_i32 s10, s10, 0x6000
	v_mov_b32_e32 v6, s10
	global_atomic_add v6, v1, s[92:93]
	buffer_inv sc1
	v_readlane_b32 s11, v244, 41
	s_sub_i32 s11, s11, s12
	s_add_i32 s11, s11, 7
	s_lshr_b32 s11, s11, 3
	s_mul_i32 s6, s11, 4
	s_branch .Lxb4_wait

.Lxb5_top:
	s_waitcnt vmcnt(0) lgkmcnt(0)
	v_mov_b32_e32 v1, 1
	v_mov_b32_e32 v0, 0x23fc0
	ds_read_b32 v2, v0
	ds_read_b32 v3, v0 offset:4
	s_getreg_b32 s12, hwreg(HW_REG_XCC_ID, 0, 4)
	s_and_b32 s12, s12, 15
	s_lshl_b32 s12, s12, 8
	s_add_i32 s10, s12, 0x1400
	s_add_i32 s12, s12, 0x2400
	v_mov_b32_e32 v5, s10
	v_mov_b32_e32 v6, s12
	global_atomic_add v7, v5, v1, s[92:93] sc0
	v_readlane_b32 s6, v244, 42
	s_add_i32 s6, s6, 1
	s_nop 0
	v_writelane_b32 v244, s6, 42
	s_waitcnt lgkmcnt(0)
	v_readfirstlane_b32 s10, v2
	v_readfirstlane_b32 s11, v3
	s_mul_i32 s10, s10, s6
	s_mul_i32 s11, s11, s6
	s_waitcnt vmcnt(0)
	v_readfirstlane_b32 s12, v7
	s_add_i32 s12, s12, 1
	s_cmp_eq_u32 s12, s10
	s_cbranch_scc0 .Lxb5_winv
	buffer_inv sc1
	buffer_wbl2 sc1
	s_waitcnt vmcnt(0)
	v_mov_b32_e32 v8, 0x3400
	global_atomic_add v7, v8, v1, s[92:93] sc0
	s_waitcnt vmcnt(0)
	v_readfirstlane_b32 s12, v7
	s_add_i32 s12, s12, 1
	s_cmp_eq_u32 s12, s11
	s_cbranch_scc0 .Lxb5_wait
	v_mov_b32_e32 v8, 0x2400
	global_atomic_add v8, v1, s[92:93]
	global_atomic_add v8, v1, s[92:93] offset:256
	global_atomic_add v8, v1, s[92:93] offset:512
	global_atomic_add v8, v1, s[92:93] offset:768
	global_atomic_add v8, v1, s[92:93] offset:1024
	global_atomic_add v8, v1, s[92:93] offset:1280
	global_atomic_add v8, v1, s[92:93] offset:1536
	global_atomic_add v8, v1, s[92:93] offset:1792
	global_atomic_add v8, v1, s[92:93] offset:2048
	global_atomic_add v8, v1, s[92:93] offset:2304
	global_atomic_add v8, v1, s[92:93] offset:2560
	global_atomic_add v8, v1, s[92:93] offset:2816
	global_atomic_add v8, v1, s[92:93] offset:3072
	global_atomic_add v8, v1, s[92:93] offset:3328
	global_atomic_add v8, v1, s[92:93] offset:3584
	global_atomic_add v8, v1, s[92:93] offset:3840
	s_branch .Lxb5_done

.Lxb6_top:
	s_waitcnt vmcnt(0) lgkmcnt(0)
	v_mov_b32_e32 v1, 1
	v_readlane_b32 s11, v244, 43
	s_cmp_eq_u32 s11, 1
	s_cbranch_scc0 .Lxb6_glob
	s_and_b32 s12, s2, 7
	s_lshl_b32 s10, s12, 8
	s_add_i32 s10, s10, 0x6000
	v_mov_b32_e32 v6, s10
	global_atomic_add v6, v1, s[92:93]
	buffer_inv sc1
	v_readlane_b32 s11, v244, 41
	s_sub_i32 s11, s11, s12
	s_add_i32 s11, s11, 7
	s_lshr_b32 s11, s11, 3
	s_mul_i32 s6, s11, 5
	s_branch .Lxb6_wait

.Lxb7_top:
	s_waitcnt vmcnt(0) lgkmcnt(0)
	v_mov_b32_e32 v1, 1
	v_readlane_b32 s11, v244, 43
	s_cmp_eq_u32 s11, 1
	s_cbranch_scc0 .Lxb7_glob
	s_and_b32 s12, s2, 7
	s_lshl_b32 s10, s12, 8
	s_add_i32 s10, s10, 0x6000
	v_mov_b32_e32 v6, s10
	global_atomic_add v6, v1, s[92:93]
	buffer_inv sc1
	v_readlane_b32 s11, v244, 41
	s_sub_i32 s11, s11, s12
	s_add_i32 s11, s11, 7
	s_lshr_b32 s11, s11, 3
	s_mul_i32 s6, s11, 6
	s_branch .Lxb7_wait

.LBB0_1062:
.Lxb8_top:
	s_endpgm
